# hg_pass x2: 16 serialized lower-bound parameter loads issued up front (one wait) instead of 8 load-wait-compute rounds, on top of kscale hoist
# baseline (speedup 1.0000x reference)
; template <int PASS  >
; __device__ __forceinline__ void hg_pass(ArgsP a, int j, int bh, int c0, int c1, unsigned char* lds) {
;     ...
;     const int c8 = wave * 2 + hi, tseg = l31;
;     float lbv[8];
; #pragma unroll
;     for (int e = 0; e < 8; ++e) { lbv[e] = 0.f; if (j == 1) { const float l0 = a->in[17][h * 128 + c8 * 8 + e], l1 = a->in[17][512 + h * 128 + c8 * 8 + e]; lbv[e] = 1.f / (1.f + expf(l0 - l1)); } }
.LBB0_793:
	s_waitcnt vmcnt(2)
	v_mov_b32_e32 v6, v224
	s_ashr_i32 s6, s7, 6
	s_lshl_b32 s4, s6, 7
	v_lshrrev_b32_e32 v1, 5, v6
	v_ashrrev_i32_e32 v7, 5, v6
	v_bfi_b32 v8, -2, v7, v1
	s_and_b32 s68, s4, 0x180
	v_lshlrev_b32_e32 v4, 3, v8
	v_add_u32_e32 v2, s68, v4
	v_cndmask_b32_e64 v3, 0, 1, s[56:57]
	v_mov_b32_e32 v1, 0
	v_cmp_ne_u32_e64 s[4:5], 1, v3
	s_andn2_b64 vcc, exec, s[56:57]
	v_ashrrev_i32_e32 v3, 31, v2
	v_ashrrev_i32_e32 v5, 31, v4
	s_cbranch_vccnz .LBB0_795
	s_load_dwordx2 s[8:9], s[0:1], 0x88
	s_waitcnt lgkmcnt(0)
	v_lshl_add_u64 v[10:11], v[2:3], 2, s[8:9]
	v_lshl_add_u64 v[12:13], v[4:5], 0, s[68:69]
	v_lshl_add_u64 v[12:13], v[12:13], 2, s[8:9]
	global_load_dword v200, v[10:11], off
	global_load_dword v201, v[12:13], off offset:2048
	global_load_dword v202, v[10:11], off offset:4
	global_load_dword v203, v[12:13], off offset:2052
	global_load_dword v204, v[10:11], off offset:8
	global_load_dword v205, v[12:13], off offset:2056
	global_load_dword v206, v[10:11], off offset:12
	global_load_dword v207, v[12:13], off offset:2060
	global_load_dword v208, v[10:11], off offset:16
	global_load_dword v209, v[12:13], off offset:2064
	global_load_dword v210, v[10:11], off offset:20
	global_load_dword v211, v[12:13], off offset:2068
	global_load_dword v212, v[10:11], off offset:24
	global_load_dword v213, v[12:13], off offset:2072
	global_load_dword v214, v[10:11], off offset:28
	global_load_dword v215, v[12:13], off offset:2076
	s_waitcnt vmcnt(0)
	v_mov_b32_e32 v1, v200
	v_mov_b32_e32 v9, v201
	s_mov_b32 s8, 0x3fb8aa3b
	v_sub_f32_e32 v1, v1, v9
	v_mul_f32_e32 v9, 0x3fb8aa3b, v1
	v_fma_f32 v10, v1, s8, -v9
	v_rndne_f32_e32 v11, v9
	v_fmac_f32_e32 v10, 0x32a5705f, v1
	v_sub_f32_e32 v9, v9, v11
	v_add_f32_e32 v9, v9, v10
	v_exp_f32_e32 v9, v9
	v_cvt_i32_f32_e32 v10, v11
	v_cmp_ngt_f32_e32 vcc, s58, v1
	s_mov_b32 s8, 0x42b17218
	v_ldexp_f32 v9, v9, v10
	v_cndmask_b32_e32 v9, 0, v9, vcc
	v_cmp_nlt_f32_e32 vcc, s8, v1
	s_nop 1
	v_cndmask_b32_e32 v1, v232, v9, vcc
	v_add_f32_e32 v1, 1.0, v1
	v_div_scale_f32 v9, s[8:9], v1, v1, 1.0
	v_rcp_f32_e32 v10, v9
	s_nop 0
	v_fma_f32 v11, -v9, v10, 1.0
	v_fmac_f32_e32 v10, v11, v10
	v_div_scale_f32 v11, vcc, 1.0, v1, 1.0
	v_mul_f32_e32 v12, v11, v10
	v_fma_f32 v13, -v9, v12, v11
	v_fmac_f32_e32 v12, v13, v10
	v_fma_f32 v9, -v9, v12, v11
	v_div_fmas_f32 v9, v9, v10, v12
	v_div_fixup_f32 v1, v9, v1, 1.0
.LBB0_795:
	s_load_dwordx2 s[16:17], s[0:1], 0xb8
	s_and_b64 vcc, exec, s[4:5]
	s_cbranch_vccnz .LBB0_797
	v_mov_b32_e32 v9, v202
	v_mov_b32_e32 v10, v203
	s_mov_b32 s8, 0x3fb8aa3b
	v_sub_f32_e32 v9, v9, v10
	v_mul_f32_e32 v10, 0x3fb8aa3b, v9
	v_fma_f32 v11, v9, s8, -v10
	v_rndne_f32_e32 v12, v10
	v_fmac_f32_e32 v11, 0x32a5705f, v9
	v_sub_f32_e32 v10, v10, v12
	v_add_f32_e32 v10, v10, v11
	v_exp_f32_e32 v10, v10
	v_cvt_i32_f32_e32 v11, v12
	v_cmp_ngt_f32_e32 vcc, s58, v9
	s_mov_b32 s8, 0x42b17218
	v_ldexp_f32 v10, v10, v11
	v_cndmask_b32_e32 v10, 0, v10, vcc
	v_cmp_nlt_f32_e32 vcc, s8, v9
	s_nop 1
	v_cndmask_b32_e32 v9, v232, v10, vcc
	v_add_f32_e32 v9, 1.0, v9
	v_div_scale_f32 v10, s[8:9], v9, v9, 1.0
	v_rcp_f32_e32 v11, v10
	s_nop 0
	v_fma_f32 v12, -v10, v11, 1.0
	v_fmac_f32_e32 v11, v12, v11
	v_div_scale_f32 v12, vcc, 1.0, v9, 1.0
	v_mul_f32_e32 v13, v12, v11
	v_fma_f32 v14, -v10, v13, v12
	v_fmac_f32_e32 v13, v14, v11
	v_fma_f32 v10, -v10, v13, v12
	v_div_fmas_f32 v10, v10, v11, v13
	v_div_fixup_f32 v76, v10, v9, 1.0
	v_mov_b32_e32 v77, 0
	s_and_b64 vcc, exec, s[4:5]
	v_mov_b32_e32 v78, 0
	s_cbranch_vccz .LBB0_798
	s_branch .LBB0_799

; template <int PASS  >
; __device__ __forceinline__ void hg_pass(ArgsP a, int j, int bh, int c0, int c1, unsigned char* lds) {
;     ...
;     for (int e = 0; e < 8; ++e) { lbv[e] = 0.f; if (j == 1) { const float l0 = a->in[17][h * 128 + c8 * 8 + e], l1 = a->in[17][512 + h * 128 + c8 * 8 + e]; lbv[e] = 1.f / (1.f + expf(l0 - l1)); } }
.LBB0_798:
	v_mov_b32_e32 v9, v204
	v_mov_b32_e32 v10, v205
	s_mov_b32 s8, 0x3fb8aa3b
	v_sub_f32_e32 v9, v9, v10
	v_mul_f32_e32 v10, 0x3fb8aa3b, v9
	v_fma_f32 v11, v9, s8, -v10
	v_rndne_f32_e32 v12, v10
	v_fmac_f32_e32 v11, 0x32a5705f, v9
	v_sub_f32_e32 v10, v10, v12
	v_add_f32_e32 v10, v10, v11
	v_exp_f32_e32 v10, v10
	v_cvt_i32_f32_e32 v11, v12
	v_cmp_ngt_f32_e32 vcc, s58, v9
	s_mov_b32 s8, 0x42b17218
	v_ldexp_f32 v10, v10, v11
	v_cndmask_b32_e32 v10, 0, v10, vcc
	v_cmp_nlt_f32_e32 vcc, s8, v9
	s_nop 1
	v_cndmask_b32_e32 v9, v232, v10, vcc
	v_add_f32_e32 v9, 1.0, v9
	v_div_scale_f32 v10, s[8:9], v9, v9, 1.0
	v_rcp_f32_e32 v11, v10
	s_nop 0
	v_fma_f32 v12, -v10, v11, 1.0
	v_fmac_f32_e32 v11, v12, v11
	v_div_scale_f32 v12, vcc, 1.0, v9, 1.0
	v_mul_f32_e32 v13, v12, v11
	v_fma_f32 v14, -v10, v13, v12
	v_fmac_f32_e32 v13, v14, v11
	v_fma_f32 v10, -v10, v13, v12
	v_div_fmas_f32 v10, v10, v11, v13
	v_div_fixup_f32 v78, v10, v9, 1.0

; template <int PASS  >
; __device__ __forceinline__ void hg_pass(ArgsP a, int j, int bh, int c0, int c1, unsigned char* lds) {
;     ...
;     for (int e = 0; e < 8; ++e) { lbv[e] = 0.f; if (j == 1) { const float l0 = a->in[17][h * 128 + c8 * 8 + e], l1 = a->in[17][512 + h * 128 + c8 * 8 + e]; lbv[e] = 1.f / (1.f + expf(l0 - l1)); } }
.LBB0_804:
	v_mov_b32_e32 v3, v214
	v_mov_b32_e32 v4, v215
	s_mov_b32 s4, 0x3fb8aa3b
	v_sub_f32_e32 v3, v3, v4
	v_mul_f32_e32 v4, 0x3fb8aa3b, v3
	v_fma_f32 v5, v3, s4, -v4
	v_rndne_f32_e32 v9, v4
	v_fmac_f32_e32 v5, 0x32a5705f, v3
	v_sub_f32_e32 v4, v4, v9
	v_add_f32_e32 v4, v4, v5
	v_exp_f32_e32 v4, v4
	v_cvt_i32_f32_e32 v5, v9
	v_cmp_ngt_f32_e32 vcc, s58, v3
	s_mov_b32 s4, 0x42b17218
	v_ldexp_f32 v4, v4, v5
	v_cndmask_b32_e32 v4, 0, v4, vcc
	v_cmp_nlt_f32_e32 vcc, s4, v3
	s_nop 1
	v_cndmask_b32_e32 v3, v232, v4, vcc
	v_add_f32_e32 v3, 1.0, v3
	v_div_scale_f32 v4, s[4:5], v3, v3, 1.0
	v_rcp_f32_e32 v5, v4
	s_nop 0
	v_fma_f32 v9, -v4, v5, 1.0
	v_fmac_f32_e32 v5, v9, v5
	v_div_scale_f32 v9, vcc, 1.0, v3, 1.0
	v_mul_f32_e32 v10, v9, v5
	v_fma_f32 v11, -v4, v10, v9
	v_fmac_f32_e32 v10, v11, v5
	v_fma_f32 v4, -v4, v10, v9
	v_div_fmas_f32 v4, v4, v5, v10
	v_div_fixup_f32 v81, v4, v3, 1.0

; template <int PASS  >
; __device__ __forceinline__ void hg_pass(ArgsP a, int j, int bh, int c0, int c1, unsigned char* lds) {
;     ...
;     for (int e = 0; e < 8; ++e) { lbv[e] = 0.f; if (j == 1) { const float l0 = a->in[17][h * 128 + c8 * 8 + e], l1 = a->in[17][512 + h * 128 + c8 * 8 + e]; lbv[e] = 1.f / (1.f + expf(l0 - l1)); } }
.LBB0_812:
	v_mov_b32_e32 v9, v206
	v_mov_b32_e32 v10, v207
	s_mov_b32 s8, 0x3fb8aa3b
	v_sub_f32_e32 v9, v9, v10
	v_mul_f32_e32 v10, 0x3fb8aa3b, v9
	v_fma_f32 v11, v9, s8, -v10
	v_rndne_f32_e32 v12, v10
	v_fmac_f32_e32 v11, 0x32a5705f, v9
	v_sub_f32_e32 v10, v10, v12
	v_add_f32_e32 v10, v10, v11
	v_exp_f32_e32 v10, v10
	v_cvt_i32_f32_e32 v11, v12
	v_cmp_ngt_f32_e32 vcc, s58, v9
	s_mov_b32 s8, 0x42b17218
	v_ldexp_f32 v10, v10, v11
	v_cndmask_b32_e32 v10, 0, v10, vcc
	v_cmp_nlt_f32_e32 vcc, s8, v9
	s_nop 1
	v_cndmask_b32_e32 v9, v232, v10, vcc
	v_add_f32_e32 v9, 1.0, v9
	v_div_scale_f32 v10, s[8:9], v9, v9, 1.0
	v_rcp_f32_e32 v11, v10
	s_nop 0
	v_fma_f32 v12, -v10, v11, 1.0
	v_fmac_f32_e32 v11, v12, v11
	v_div_scale_f32 v12, vcc, 1.0, v9, 1.0
	v_mul_f32_e32 v13, v12, v11
	v_fma_f32 v14, -v10, v13, v12
	v_fmac_f32_e32 v13, v14, v11
	v_fma_f32 v10, -v10, v13, v12
	v_div_fmas_f32 v10, v10, v11, v13
	v_div_fixup_f32 v77, v10, v9, 1.0
	v_mov_b32_e32 v79, 0
	s_and_b64 vcc, exec, s[4:5]
	v_mov_b32_e32 v80, 0
	s_cbranch_vccnz .LBB0_801
.LBB0_813:
	v_mov_b32_e32 v9, v208
	v_mov_b32_e32 v10, v209
	s_mov_b32 s8, 0x3fb8aa3b
	v_sub_f32_e32 v9, v9, v10
	v_mul_f32_e32 v10, 0x3fb8aa3b, v9
	v_fma_f32 v11, v9, s8, -v10
	v_rndne_f32_e32 v12, v10
	v_fmac_f32_e32 v11, 0x32a5705f, v9
	v_sub_f32_e32 v10, v10, v12
	v_add_f32_e32 v10, v10, v11
	v_exp_f32_e32 v10, v10
	v_cvt_i32_f32_e32 v11, v12
	v_cmp_ngt_f32_e32 vcc, s58, v9
	s_mov_b32 s8, 0x42b17218
	v_ldexp_f32 v10, v10, v11
	v_cndmask_b32_e32 v10, 0, v10, vcc
	v_cmp_nlt_f32_e32 vcc, s8, v9
	s_nop 1
	v_cndmask_b32_e32 v9, v232, v10, vcc
	v_add_f32_e32 v9, 1.0, v9
	v_div_scale_f32 v10, s[8:9], v9, v9, 1.0
	v_rcp_f32_e32 v11, v10
	s_nop 0
	v_fma_f32 v12, -v10, v11, 1.0
	v_fmac_f32_e32 v11, v12, v11
	v_div_scale_f32 v12, vcc, 1.0, v9, 1.0
	v_mul_f32_e32 v13, v12, v11
	v_fma_f32 v14, -v10, v13, v12
	v_fmac_f32_e32 v13, v14, v11
	v_fma_f32 v10, -v10, v13, v12
	v_div_fmas_f32 v10, v10, v11, v13
	v_div_fixup_f32 v80, v10, v9, 1.0
	s_and_b64 vcc, exec, s[4:5]
	s_cbranch_vccnz .LBB0_802
.LBB0_814:
	v_mov_b32_e32 v9, v210
	v_mov_b32_e32 v10, v211
	s_mov_b32 s8, 0x3fb8aa3b
	v_sub_f32_e32 v9, v9, v10
	v_mul_f32_e32 v10, 0x3fb8aa3b, v9
	v_fma_f32 v11, v9, s8, -v10
	v_rndne_f32_e32 v12, v10
	v_fmac_f32_e32 v11, 0x32a5705f, v9
	v_sub_f32_e32 v10, v10, v12
	v_add_f32_e32 v10, v10, v11
	v_exp_f32_e32 v10, v10
	v_cvt_i32_f32_e32 v11, v12
	v_cmp_ngt_f32_e32 vcc, s58, v9
	s_mov_b32 s8, 0x42b17218
	v_ldexp_f32 v10, v10, v11
	v_cndmask_b32_e32 v10, 0, v10, vcc
	v_cmp_nlt_f32_e32 vcc, s8, v9
	s_nop 1
	v_cndmask_b32_e32 v9, v232, v10, vcc
	v_add_f32_e32 v9, 1.0, v9
	v_div_scale_f32 v10, s[8:9], v9, v9, 1.0
	v_rcp_f32_e32 v11, v10
	s_nop 0
	v_fma_f32 v12, -v10, v11, 1.0
	v_fmac_f32_e32 v11, v12, v11
	v_div_scale_f32 v12, vcc, 1.0, v9, 1.0
	v_mul_f32_e32 v13, v12, v11
	v_fma_f32 v14, -v10, v13, v12
	v_fmac_f32_e32 v13, v14, v11
	v_fma_f32 v10, -v10, v13, v12
	v_div_fmas_f32 v10, v10, v11, v13
	v_div_fixup_f32 v79, v10, v9, 1.0
	v_mov_b32_e32 v81, 0
	s_and_b64 vcc, exec, s[4:5]
	v_mov_b32_e32 v82, 0
	s_cbranch_vccnz .LBB0_803
.LBB0_815:
	v_mov_b32_e32 v9, v212
	v_mov_b32_e32 v10, v213
	s_mov_b32 s8, 0x3fb8aa3b
	v_sub_f32_e32 v9, v9, v10
	v_mul_f32_e32 v10, 0x3fb8aa3b, v9
	v_fma_f32 v11, v9, s8, -v10
	v_rndne_f32_e32 v12, v10
	v_fmac_f32_e32 v11, 0x32a5705f, v9
	v_sub_f32_e32 v10, v10, v12
	v_add_f32_e32 v10, v10, v11
	v_exp_f32_e32 v10, v10
	v_cvt_i32_f32_e32 v11, v12
	v_cmp_ngt_f32_e32 vcc, s58, v9
	s_mov_b32 s8, 0x42b17218
	v_ldexp_f32 v10, v10, v11
	v_cndmask_b32_e32 v10, 0, v10, vcc
	v_cmp_nlt_f32_e32 vcc, s8, v9
	s_nop 1
	v_cndmask_b32_e32 v9, v232, v10, vcc
	v_add_f32_e32 v9, 1.0, v9
	v_div_scale_f32 v10, s[8:9], v9, v9, 1.0
	v_rcp_f32_e32 v11, v10
	s_nop 0
	v_fma_f32 v12, -v10, v11, 1.0
	v_fmac_f32_e32 v11, v12, v11
	v_div_scale_f32 v12, vcc, 1.0, v9, 1.0
	v_mul_f32_e32 v13, v12, v11
	v_fma_f32 v14, -v10, v13, v12
	v_fmac_f32_e32 v13, v14, v11
	v_fma_f32 v10, -v10, v13, v12
	v_div_fmas_f32 v10, v10, v11, v13
	v_div_fixup_f32 v82, v10, v9, 1.0
	s_and_b64 vcc, exec, s[4:5]
	s_cbranch_vccz .LBB0_804
	s_branch .LBB0_805

; template <int PASS  >
; __device__ __forceinline__ void hg_pass(ArgsP a, int j, int bh, int c0, int c1, unsigned char* lds) {
;     ...
;     const int c8 = wave * 2 + hi, tseg = l31;
;     float lbv[8];
; #pragma unroll
;     for (int e = 0; e < 8; ++e) { lbv[e] = 0.f; if (j == 1) { const float l0 = a->in[17][h * 128 + c8 * 8 + e], l1 = a->in[17][512 + h * 128 + c8 * 8 + e]; lbv[e] = 1.f / (1.f + expf(l0 - l1)); } }
.LBB0_955:
	v_mov_b32_e32 v83, v224
	s_ashr_i32 s6, s33, 6
	s_and_b32 s14, s6, 3
	v_ashrrev_i32_e32 v84, 6, v83
	v_bfe_u32 v85, v83, 5, 1
	v_lshl_or_b32 v82, v84, 1, v85
	s_lshl_b32 s10, s14, 7
	s_waitcnt vmcnt(9)
	v_lshlrev_b32_e32 v44, 3, v82
	v_add_u32_e32 v42, s10, v44
	v_cndmask_b32_e64 v1, 0, 1, s[56:57]
	v_mov_b32_e32 v18, 0
	v_cmp_ne_u32_e64 s[4:5], 1, v1
	s_andn2_b64 vcc, exec, s[56:57]
	v_ashrrev_i32_e32 v43, 31, v42
	v_ashrrev_i32_e32 v45, 31, v44
	s_cbranch_vccnz .LBB0_957
	s_load_dwordx2 s[8:9], s[0:1], 0x88
	s_mov_b32 s11, s69
	v_lshl_add_u64 v[2:3], v[44:45], 0, s[10:11]
	s_mov_b32 s7, 0x3fb8aa3b
	s_waitcnt lgkmcnt(0)
	v_lshl_add_u64 v[4:5], v[42:43], 2, s[8:9]
	v_lshl_add_u64 v[2:3], v[2:3], 2, s[8:9]
	global_load_dword v216, v[4:5], off
	global_load_dword v217, v[2:3], off offset:2048
	global_load_dword v218, v[4:5], off offset:4
	global_load_dword v219, v[2:3], off offset:2052
	global_load_dword v220, v[4:5], off offset:8
	global_load_dword v221, v[2:3], off offset:2056
	global_load_dword v222, v[4:5], off offset:12
	global_load_dword v223, v[2:3], off offset:2060
	global_load_dword v239, v[4:5], off offset:16
	global_load_dword v240, v[2:3], off offset:2064
	global_load_dword v241, v[4:5], off offset:20
	global_load_dword v242, v[2:3], off offset:2068
	global_load_dword v243, v[4:5], off offset:24
	global_load_dword v244, v[2:3], off offset:2072
	global_load_dword v245, v[4:5], off offset:28
	global_load_dword v246, v[2:3], off offset:2076
	s_nop 0
	s_waitcnt vmcnt(0)
	v_mov_b32_e32 v1, v216
	v_mov_b32_e32 v2, v217
	v_sub_f32_e32 v1, v1, v2
	v_mul_f32_e32 v2, 0x3fb8aa3b, v1
	v_fma_f32 v3, v1, s7, -v2
	v_rndne_f32_e32 v4, v2
	v_fmac_f32_e32 v3, 0x32a5705f, v1
	v_sub_f32_e32 v2, v2, v4
	v_add_f32_e32 v2, v2, v3
	v_cvt_i32_f32_e32 v4, v4
	v_exp_f32_e32 v2, v2
	v_cmp_ngt_f32_e32 vcc, s58, v1
	s_mov_b32 s7, 0x42b17218
	v_ldexp_f32 v2, v2, v4
	v_cndmask_b32_e32 v2, 0, v2, vcc
	v_cmp_nlt_f32_e32 vcc, s7, v1
	s_nop 1
	v_cndmask_b32_e32 v1, v232, v2, vcc
	v_add_f32_e32 v1, 1.0, v1
	v_div_scale_f32 v2, s[8:9], v1, v1, 1.0
	v_rcp_f32_e32 v3, v2
	v_div_scale_f32 v4, vcc, 1.0, v1, 1.0
	v_fma_f32 v5, -v2, v3, 1.0
	v_fmac_f32_e32 v3, v5, v3
	v_mul_f32_e32 v5, v4, v3
	v_fma_f32 v6, -v2, v5, v4
	v_fmac_f32_e32 v5, v6, v3
	v_fma_f32 v2, -v2, v5, v4
	v_div_fmas_f32 v2, v2, v3, v5
	v_div_fixup_f32 v18, v2, v1, 1.0
.LBB0_957:
	s_load_dwordx2 s[8:9], s[0:1], 0x90
	s_load_dwordx2 s[52:53], s[0:1], 0xb8
	s_and_b64 vcc, exec, s[4:5]
	s_cbranch_vccnz .LBB0_959
	s_load_dwordx2 s[12:13], s[0:1], 0x88
	s_mov_b32 s11, s69
	v_lshl_add_u64 v[2:3], v[44:45], 0, s[10:11]
	s_mov_b32 s7, 0x3fb8aa3b
	v_mov_b32_e32 v24, s69
	s_waitcnt lgkmcnt(0)
	v_lshl_add_u64 v[4:5], v[42:43], 2, s[12:13]
	v_lshl_add_u64 v[2:3], v[2:3], 2, s[12:13]
	v_mov_b32_e32 v1, v218
	s_nop 0
	v_mov_b32_e32 v2, v219
	v_mov_b32_e32 v25, s69
	v_mov_b32_e32 v20, s69
	v_mov_b32_e32 v21, s69
	v_mov_b32_e32 v22, s69
	v_mov_b32_e32 v23, s69
	s_waitcnt vmcnt(0)
	v_sub_f32_e32 v1, v1, v2
	v_mul_f32_e32 v2, 0x3fb8aa3b, v1
	v_fma_f32 v3, v1, s7, -v2
	v_rndne_f32_e32 v4, v2
	v_fmac_f32_e32 v3, 0x32a5705f, v1
	v_sub_f32_e32 v2, v2, v4
	v_add_f32_e32 v2, v2, v3
	v_cvt_i32_f32_e32 v4, v4
	v_exp_f32_e32 v2, v2
	v_cmp_ngt_f32_e32 vcc, s58, v1
	s_mov_b32 s7, 0x42b17218
	v_ldexp_f32 v2, v2, v4
	v_cndmask_b32_e32 v2, 0, v2, vcc
	v_cmp_nlt_f32_e32 vcc, s7, v1
	s_nop 1
	v_cndmask_b32_e32 v1, v232, v2, vcc
	v_add_f32_e32 v1, 1.0, v1
	v_div_scale_f32 v2, s[12:13], v1, v1, 1.0
	v_rcp_f32_e32 v3, v2
	v_div_scale_f32 v4, vcc, 1.0, v1, 1.0
	v_fma_f32 v5, -v2, v3, 1.0
	v_fmac_f32_e32 v3, v5, v3
	v_mul_f32_e32 v5, v4, v3
	v_fma_f32 v6, -v2, v5, v4
	v_fmac_f32_e32 v5, v6, v3
	v_fma_f32 v2, -v2, v5, v4
	v_div_fmas_f32 v2, v2, v3, v5
	v_div_fixup_f32 v19, v2, v1, 1.0
	v_mov_b64_e32 v[2:3], v[18:19]
	v_mov_b64_e32 v[10:11], v[18:19]
	v_mov_b64_e32 v[32:33], v[24:25]
	v_mov_b64_e32 v[40:41], v[24:25]
	v_mov_b64_e32 v[4:5], v[20:21]
	v_mov_b64_e32 v[6:7], v[22:23]
	v_mov_b64_e32 v[8:9], v[24:25]
	v_mov_b64_e32 v[12:13], v[20:21]
	v_mov_b64_e32 v[14:15], v[22:23]
	v_mov_b64_e32 v[16:17], v[24:25]
	v_mov_b64_e32 v[30:31], v[22:23]
	v_mov_b64_e32 v[28:29], v[20:21]
	v_mov_b64_e32 v[26:27], v[18:19]
	v_mov_b64_e32 v[38:39], v[22:23]
	v_mov_b64_e32 v[36:37], v[20:21]
	v_mov_b64_e32 v[34:35], v[18:19]
	v_mov_b32_e32 v1, v19
	v_mov_b32_e32 v122, 0
	s_and_b64 vcc, exec, s[4:5]
	v_mov_b32_e32 v123, 0
	s_cbranch_vccz .LBB0_960
	s_branch .LBB0_961

; template <int PASS  >
; __device__ __forceinline__ void hg_pass(ArgsP a, int j, int bh, int c0, int c1, unsigned char* lds) {
;     ...
;     for (int e = 0; e < 8; ++e) { lbv[e] = 0.f; if (j == 1) { const float l0 = a->in[17][h * 128 + c8 * 8 + e], l1 = a->in[17][512 + h * 128 + c8 * 8 + e]; lbv[e] = 1.f / (1.f + expf(l0 - l1)); } }
.LBB0_960:
	s_load_dwordx2 s[12:13], s[0:1], 0x88
	s_mov_b32 s11, s69
	v_lshl_add_u64 v[2:3], v[44:45], 0, s[10:11]
	s_mov_b32 s7, 0x3fb8aa3b
	v_mov_b32_e32 v21, s69
	s_waitcnt lgkmcnt(0)
	v_lshl_add_u64 v[4:5], v[42:43], 2, s[12:13]
	v_lshl_add_u64 v[2:3], v[2:3], 2, s[12:13]
	v_mov_b32_e32 v4, v220
	s_nop 0
	v_mov_b32_e32 v2, v221
	s_waitcnt vmcnt(0)
	v_sub_f32_e32 v2, v4, v2
	v_mul_f32_e32 v3, 0x3fb8aa3b, v2
	v_fma_f32 v4, v2, s7, -v3
	v_rndne_f32_e32 v5, v3
	v_fmac_f32_e32 v4, 0x32a5705f, v2
	v_sub_f32_e32 v3, v3, v5
	v_add_f32_e32 v3, v3, v4
	v_cvt_i32_f32_e32 v5, v5
	v_exp_f32_e32 v3, v3
	v_cmp_ngt_f32_e32 vcc, s58, v2
	s_mov_b32 s7, 0x42b17218
	v_ldexp_f32 v3, v3, v5
	v_cndmask_b32_e32 v3, 0, v3, vcc
	v_cmp_nlt_f32_e32 vcc, s7, v2
	s_nop 1
	v_cndmask_b32_e32 v2, v232, v3, vcc
	v_add_f32_e32 v2, 1.0, v2
	v_div_scale_f32 v3, s[12:13], v2, v2, 1.0
	v_rcp_f32_e32 v4, v3
	v_div_scale_f32 v5, vcc, 1.0, v2, 1.0
	v_fma_f32 v6, -v3, v4, 1.0
	v_fmac_f32_e32 v4, v6, v4
	v_mul_f32_e32 v6, v5, v4
	v_fma_f32 v7, -v3, v6, v5
	v_fmac_f32_e32 v6, v7, v4
	v_fma_f32 v3, -v3, v6, v5
	v_div_fmas_f32 v3, v3, v4, v6
	v_div_fixup_f32 v20, v3, v2, 1.0
	v_mov_b64_e32 v[40:41], v[24:25]
	v_mov_b64_e32 v[38:39], v[22:23]
	v_mov_b64_e32 v[34:35], v[18:19]
	v_mov_b64_e32 v[36:37], v[20:21]
	v_mov_b32_e32 v38, s69
	v_mov_b64_e32 v[26:27], v[34:35]
	v_mov_b64_e32 v[30:31], v[38:39]
	v_mov_b64_e32 v[28:29], v[36:37]
	v_mov_b64_e32 v[32:33], v[40:41]
	v_mov_b32_e32 v31, s69
	v_mov_b64_e32 v[10:11], v[26:27]
	v_mov_b64_e32 v[16:17], v[32:33]
	v_mov_b64_e32 v[12:13], v[28:29]
	v_mov_b64_e32 v[14:15], v[30:31]
	v_mov_b32_e32 v16, s69
	v_mov_b64_e32 v[2:3], v[10:11]
	v_mov_b64_e32 v[8:9], v[16:17]
	v_mov_b64_e32 v[4:5], v[12:13]
	v_mov_b64_e32 v[6:7], v[14:15]
	v_mov_b32_e32 v9, s69
	v_mov_b32_e32 v123, v20

; template <int PASS  >
; __device__ __forceinline__ void hg_pass(ArgsP a, int j, int bh, int c0, int c1, unsigned char* lds) {
;     ...
;     for (int e = 0; e < 8; ++e) { lbv[e] = 0.f; if (j == 1) { const float l0 = a->in[17][h * 128 + c8 * 8 + e], l1 = a->in[17][512 + h * 128 + c8 * 8 + e]; lbv[e] = 1.f / (1.f + expf(l0 - l1)); } }
.LBB0_966:
	s_load_dwordx2 s[4:5], s[0:1], 0x88
	s_mov_b32 s11, s69
	v_lshl_add_u64 v[2:3], v[44:45], 0, s[10:11]
	s_waitcnt lgkmcnt(0)
	v_lshl_add_u64 v[4:5], v[42:43], 2, s[4:5]
	v_lshl_add_u64 v[2:3], v[2:3], 2, s[4:5]
	v_mov_b32_e32 v4, v245
	s_nop 0
	v_mov_b32_e32 v2, v246
	s_mov_b32 s4, 0x3fb8aa3b
	s_waitcnt vmcnt(0)
	v_sub_f32_e32 v2, v4, v2
	v_mul_f32_e32 v3, 0x3fb8aa3b, v2
	v_fma_f32 v4, v2, s4, -v3
	v_rndne_f32_e32 v5, v3
	v_fmac_f32_e32 v4, 0x32a5705f, v2
	v_sub_f32_e32 v3, v3, v5
	v_add_f32_e32 v3, v3, v4
	v_cvt_i32_f32_e32 v5, v5
	v_exp_f32_e32 v3, v3
	v_cmp_ngt_f32_e32 vcc, s58, v2
	s_mov_b32 s4, 0x42b17218
	v_ldexp_f32 v3, v3, v5
	v_cndmask_b32_e32 v3, 0, v3, vcc
	v_cmp_nlt_f32_e32 vcc, s4, v2
	s_nop 1
	v_cndmask_b32_e32 v2, v232, v3, vcc
	v_add_f32_e32 v2, 1.0, v2
	v_div_scale_f32 v3, s[4:5], v2, v2, 1.0
	v_rcp_f32_e32 v4, v3
	v_div_scale_f32 v5, vcc, 1.0, v2, 1.0
	v_fma_f32 v6, -v3, v4, 1.0
	v_fmac_f32_e32 v4, v6, v4
	v_mul_f32_e32 v6, v5, v4
	v_fma_f32 v7, -v3, v6, v5
	v_fmac_f32_e32 v6, v7, v4
	v_fma_f32 v3, -v3, v6, v5
	v_div_fmas_f32 v3, v3, v4, v6
	v_div_fixup_f32 v17, v3, v2, 1.0
	v_mov_b64_e32 v[2:3], v[10:11]
	v_mov_b64_e32 v[4:5], v[12:13]
	v_mov_b64_e32 v[6:7], v[14:15]
	v_mov_b64_e32 v[8:9], v[16:17]
	v_mov_b32_e32 v19, v17

; template <int PASS  >
; __device__ __forceinline__ void hg_pass(ArgsP a, int j, int bh, int c0, int c1, unsigned char* lds) {
;     ...
;     for (int e = 0; e < 8; ++e) { lbv[e] = 0.f; if (j == 1) { const float l0 = a->in[17][h * 128 + c8 * 8 + e], l1 = a->in[17][512 + h * 128 + c8 * 8 + e]; lbv[e] = 1.f / (1.f + expf(l0 - l1)); } }
.LBB0_985:
	s_load_dwordx2 s[12:13], s[0:1], 0x88
	s_mov_b32 s11, s69
	v_lshl_add_u64 v[2:3], v[44:45], 0, s[10:11]
	s_mov_b32 s7, 0x3fb8aa3b
	s_waitcnt lgkmcnt(0)
	v_lshl_add_u64 v[4:5], v[42:43], 2, s[12:13]
	v_lshl_add_u64 v[2:3], v[2:3], 2, s[12:13]
	v_mov_b32_e32 v4, v222
	s_nop 0
	v_mov_b32_e32 v2, v223
	s_waitcnt vmcnt(0)
	v_sub_f32_e32 v2, v4, v2
	v_mul_f32_e32 v3, 0x3fb8aa3b, v2
	v_fma_f32 v4, v2, s7, -v3
	v_rndne_f32_e32 v5, v3
	v_fmac_f32_e32 v4, 0x32a5705f, v2
	v_sub_f32_e32 v3, v3, v5
	v_add_f32_e32 v3, v3, v4
	v_cvt_i32_f32_e32 v5, v5
	v_exp_f32_e32 v3, v3
	v_cmp_ngt_f32_e32 vcc, s58, v2
	s_mov_b32 s7, 0x42b17218
	v_ldexp_f32 v3, v3, v5
	v_cndmask_b32_e32 v3, 0, v3, vcc
	v_cmp_nlt_f32_e32 vcc, s7, v2
	s_nop 1
	v_cndmask_b32_e32 v2, v232, v3, vcc
	v_add_f32_e32 v2, 1.0, v2
	v_div_scale_f32 v3, s[12:13], v2, v2, 1.0
	v_rcp_f32_e32 v4, v3
	v_div_scale_f32 v5, vcc, 1.0, v2, 1.0
	v_fma_f32 v6, -v3, v4, 1.0
	v_fmac_f32_e32 v4, v6, v4
	v_mul_f32_e32 v6, v5, v4
	v_fma_f32 v7, -v3, v6, v5
	v_fmac_f32_e32 v6, v7, v4
	v_fma_f32 v3, -v3, v6, v5
	v_div_fmas_f32 v3, v3, v4, v6
	v_div_fixup_f32 v21, v3, v2, 1.0
	v_mov_b64_e32 v[40:41], v[24:25]
	v_mov_b64_e32 v[38:39], v[22:23]
	v_mov_b64_e32 v[34:35], v[18:19]
	v_mov_b64_e32 v[36:37], v[20:21]
	v_mov_b32_e32 v38, s69
	v_mov_b64_e32 v[26:27], v[34:35]
	v_mov_b64_e32 v[30:31], v[38:39]
	v_mov_b64_e32 v[28:29], v[36:37]
	v_mov_b64_e32 v[32:33], v[40:41]
	v_mov_b32_e32 v31, s69
	v_mov_b64_e32 v[10:11], v[26:27]
	v_mov_b64_e32 v[16:17], v[32:33]
	v_mov_b64_e32 v[12:13], v[28:29]
	v_mov_b64_e32 v[14:15], v[30:31]
	v_mov_b32_e32 v16, s69
	v_mov_b64_e32 v[2:3], v[10:11]
	v_mov_b64_e32 v[8:9], v[16:17]
	v_mov_b64_e32 v[4:5], v[12:13]
	v_mov_b64_e32 v[6:7], v[14:15]
	v_mov_b32_e32 v9, s69
	v_mov_b32_e32 v122, v21
	v_mov_b32_e32 v124, 0
	s_and_b64 vcc, exec, s[4:5]
	v_mov_b32_e32 v22, 0
	s_cbranch_vccnz .LBB0_963
.LBB0_986:
	s_load_dwordx2 s[12:13], s[0:1], 0x88
	s_mov_b32 s11, s69
	v_lshl_add_u64 v[2:3], v[44:45], 0, s[10:11]
	s_mov_b32 s7, 0x3fb8aa3b
	s_waitcnt lgkmcnt(0)
	v_lshl_add_u64 v[4:5], v[42:43], 2, s[12:13]
	v_lshl_add_u64 v[2:3], v[2:3], 2, s[12:13]
	v_mov_b32_e32 v4, v239
	s_nop 0
	v_mov_b32_e32 v2, v240
	s_waitcnt vmcnt(0)
	v_sub_f32_e32 v2, v4, v2
	v_mul_f32_e32 v3, 0x3fb8aa3b, v2
	v_fma_f32 v4, v2, s7, -v3
	v_rndne_f32_e32 v5, v3
	v_fmac_f32_e32 v4, 0x32a5705f, v2
	v_sub_f32_e32 v3, v3, v5
	v_add_f32_e32 v3, v3, v4
	v_cvt_i32_f32_e32 v5, v5
	v_exp_f32_e32 v3, v3
	v_cmp_ngt_f32_e32 vcc, s58, v2
	s_mov_b32 s7, 0x42b17218
	v_ldexp_f32 v3, v3, v5
	v_cndmask_b32_e32 v3, 0, v3, vcc
	v_cmp_nlt_f32_e32 vcc, s7, v2
	s_nop 1
	v_cndmask_b32_e32 v2, v232, v3, vcc
	v_add_f32_e32 v2, 1.0, v2
	v_div_scale_f32 v3, s[12:13], v2, v2, 1.0
	v_rcp_f32_e32 v4, v3
	v_div_scale_f32 v5, vcc, 1.0, v2, 1.0
	v_fma_f32 v6, -v3, v4, 1.0
	v_fmac_f32_e32 v4, v6, v4
	v_mul_f32_e32 v6, v5, v4
	v_fma_f32 v7, -v3, v6, v5
	v_fmac_f32_e32 v6, v7, v4
	v_fma_f32 v3, -v3, v6, v5
	v_div_fmas_f32 v3, v3, v4, v6
	v_div_fixup_f32 v22, v3, v2, 1.0
	v_mov_b64_e32 v[32:33], v[24:25]
	v_mov_b64_e32 v[30:31], v[22:23]
	v_mov_b64_e32 v[26:27], v[18:19]
	v_mov_b64_e32 v[28:29], v[20:21]
	v_mov_b32_e32 v31, s69
	v_mov_b64_e32 v[10:11], v[26:27]
	v_mov_b64_e32 v[16:17], v[32:33]
	v_mov_b64_e32 v[12:13], v[28:29]
	v_mov_b64_e32 v[14:15], v[30:31]
	v_mov_b32_e32 v16, s69
	v_mov_b64_e32 v[2:3], v[10:11]
	v_mov_b64_e32 v[8:9], v[16:17]
	v_mov_b64_e32 v[40:41], v[24:25]
	v_mov_b64_e32 v[4:5], v[12:13]
	v_mov_b64_e32 v[6:7], v[14:15]
	v_mov_b32_e32 v9, s69
	v_mov_b64_e32 v[38:39], v[22:23]
	v_mov_b64_e32 v[36:37], v[20:21]
	v_mov_b64_e32 v[34:35], v[18:19]
	s_and_b64 vcc, exec, s[4:5]
	s_cbranch_vccnz .LBB0_964
.LBB0_987:
	s_load_dwordx2 s[12:13], s[0:1], 0x88
	s_mov_b32 s11, s69
	v_lshl_add_u64 v[2:3], v[44:45], 0, s[10:11]
	s_mov_b32 s7, 0x3fb8aa3b
	s_waitcnt lgkmcnt(0)
	v_lshl_add_u64 v[4:5], v[42:43], 2, s[12:13]
	v_lshl_add_u64 v[2:3], v[2:3], 2, s[12:13]
	v_mov_b32_e32 v4, v241
	s_nop 0
	v_mov_b32_e32 v2, v242
	s_waitcnt vmcnt(0)
	v_sub_f32_e32 v2, v4, v2
	v_mul_f32_e32 v3, 0x3fb8aa3b, v2
	v_fma_f32 v4, v2, s7, -v3
	v_rndne_f32_e32 v5, v3
	v_fmac_f32_e32 v4, 0x32a5705f, v2
	v_sub_f32_e32 v3, v3, v5
	v_add_f32_e32 v3, v3, v4
	v_cvt_i32_f32_e32 v5, v5
	v_exp_f32_e32 v3, v3
	v_cmp_ngt_f32_e32 vcc, s58, v2
	s_mov_b32 s7, 0x42b17218
	v_ldexp_f32 v3, v3, v5
	v_cndmask_b32_e32 v3, 0, v3, vcc
	v_cmp_nlt_f32_e32 vcc, s7, v2
	s_nop 1
	v_cndmask_b32_e32 v2, v232, v3, vcc
	v_add_f32_e32 v2, 1.0, v2
	v_div_scale_f32 v3, s[12:13], v2, v2, 1.0
	v_rcp_f32_e32 v4, v3
	v_div_scale_f32 v5, vcc, 1.0, v2, 1.0
	v_fma_f32 v6, -v3, v4, 1.0
	v_fmac_f32_e32 v4, v6, v4
	v_mul_f32_e32 v6, v5, v4
	v_fma_f32 v7, -v3, v6, v5
	v_fmac_f32_e32 v6, v7, v4
	v_fma_f32 v3, -v3, v6, v5
	v_div_fmas_f32 v3, v3, v4, v6
	v_div_fixup_f32 v39, v3, v2, 1.0
	v_mov_b64_e32 v[10:11], v[34:35]
	v_mov_b64_e32 v[16:17], v[40:41]
	v_mov_b64_e32 v[12:13], v[36:37]
	v_mov_b64_e32 v[14:15], v[38:39]
	v_mov_b32_e32 v16, s69
	v_mov_b64_e32 v[2:3], v[10:11]
	v_mov_b64_e32 v[26:27], v[34:35]
	v_mov_b64_e32 v[8:9], v[16:17]
	v_mov_b64_e32 v[28:29], v[36:37]
	v_mov_b64_e32 v[30:31], v[38:39]
	v_mov_b64_e32 v[32:33], v[40:41]
	v_mov_b64_e32 v[4:5], v[12:13]
	v_mov_b64_e32 v[6:7], v[14:15]
	v_mov_b32_e32 v9, s69
	v_mov_b32_e32 v124, v39
	v_mov_b32_e32 v19, 0
	s_and_b64 vcc, exec, s[4:5]
	v_mov_b32_e32 v32, 0
	s_cbranch_vccnz .LBB0_965
.LBB0_988:
	s_load_dwordx2 s[12:13], s[0:1], 0x88
	s_mov_b32 s11, s69
	v_lshl_add_u64 v[2:3], v[44:45], 0, s[10:11]
	s_mov_b32 s7, 0x3fb8aa3b
	s_waitcnt lgkmcnt(0)
	v_lshl_add_u64 v[4:5], v[42:43], 2, s[12:13]
	v_lshl_add_u64 v[2:3], v[2:3], 2, s[12:13]
	v_mov_b32_e32 v4, v243
	s_nop 0
	v_mov_b32_e32 v2, v244
	s_waitcnt vmcnt(0)
	v_sub_f32_e32 v2, v4, v2
	v_mul_f32_e32 v3, 0x3fb8aa3b, v2
	v_fma_f32 v4, v2, s7, -v3
	v_rndne_f32_e32 v5, v3
	v_fmac_f32_e32 v4, 0x32a5705f, v2
	v_sub_f32_e32 v3, v3, v5
	v_add_f32_e32 v3, v3, v4
	v_cvt_i32_f32_e32 v5, v5
	v_exp_f32_e32 v3, v3
	v_cmp_ngt_f32_e32 vcc, s58, v2
	s_mov_b32 s7, 0x42b17218
	v_ldexp_f32 v3, v3, v5
	v_cndmask_b32_e32 v3, 0, v3, vcc
	v_cmp_nlt_f32_e32 vcc, s7, v2
	s_nop 1
	v_cndmask_b32_e32 v2, v232, v3, vcc
	v_add_f32_e32 v2, 1.0, v2
	v_div_scale_f32 v3, s[12:13], v2, v2, 1.0
	v_rcp_f32_e32 v4, v3
	v_div_scale_f32 v5, vcc, 1.0, v2, 1.0
	v_fma_f32 v6, -v3, v4, 1.0
	v_fmac_f32_e32 v4, v6, v4
	v_mul_f32_e32 v6, v5, v4
	v_fma_f32 v7, -v3, v6, v5
	v_fmac_f32_e32 v6, v7, v4
	v_fma_f32 v3, -v3, v6, v5
	v_div_fmas_f32 v3, v3, v4, v6
	v_div_fixup_f32 v32, v3, v2, 1.0
	v_mov_b64_e32 v[2:3], v[26:27]
	v_mov_b64_e32 v[8:9], v[32:33]
	v_mov_b64_e32 v[10:11], v[26:27]
	v_mov_b64_e32 v[4:5], v[28:29]
	v_mov_b64_e32 v[6:7], v[30:31]
	v_mov_b32_e32 v9, s69
	v_mov_b64_e32 v[12:13], v[28:29]
	v_mov_b64_e32 v[14:15], v[30:31]
	v_mov_b64_e32 v[16:17], v[32:33]
	s_and_b64 vcc, exec, s[4:5]
	s_cbranch_vccz .LBB0_966
	s_branch .LBB0_967
